# attention inst1 K/V tile loads via SGPR base + 32-bit lane offsets, pointer advance on SALU in chain slots
# speedup vs baseline: 1.0207x; 1.0010x over previous
; template <bool SAMPLE> __device__ __forceinline__ void attn_unit16(const Ctx& c, LAS unsigned char* lds, int b, int h, int qb, int wave_s) {
;     ...
;         if (!SAMPLE) {
;             const int kidx0 = j == 0 ? 0 : 16 + 64 * (j - 1);
;             const size_t rr = (size_t)(b * 8 + h) * KROWS + kidx0 + lrow;
;             const bf16* p = (const bf16*)(ws + (isk ? WS_DK : WS_DV)) + rr * 128;
;             r0 = *(const u32x4*)(p + lck * 8); r1 = *(const u32x4*)(p + 64 + lck * 8);
.LBB0_835:
	v_exp_f32_e32 v50, v42
	v_exp_f32_e32 v51, v38
	v_exp_f32_e32 v52, v43
	v_exp_f32_e32 v53, v39
	v_exp_f32_e32 v54, v40
	v_exp_f32_e32 v55, v36
	v_exp_f32_e32 v56, v41
	v_exp_f32_e32 v57, v37
	v_exp_f32_e32 v58, v46
	v_exp_f32_e32 v59, v0
	v_pk_add_f32 v[36:37], v[50:51], 0 op_sel_hi:[1,0]
	v_exp_f32_e32 v64, v46
	v_exp_f32_e32 v65, v47
	v_pk_add_f32 v[36:37], v[52:53], v[36:37]
	v_exp_f32_e32 v66, v46
	v_exp_f32_e32 v67, v48
	v_pk_add_f32 v[36:37], v[54:55], v[36:37]
	v_exp_f32_e32 v46, v46
	v_exp_f32_e32 v47, v49
	v_pk_add_f32 v[36:37], v[56:57], v[36:37]
	v_lshrrev_b32_e32 v68, 2, v45
	v_pk_add_f32 v[36:37], v[58:59], v[36:37]
	v_lshlrev_b32_e32 v69, 2, v210
	v_pk_add_f32 v[36:37], v[64:65], v[36:37]
	v_or_b32_e32 v0, v69, v68
	v_pk_add_f32 v[36:37], v[66:67], v[36:37]
	s_lshl_b32 s82, s2, 1
	v_pk_add_f32 v[36:37], v[46:47], v[36:37]
	v_mul_u32_u24_e32 v0, 0x120, v0
	v_pk_add_f32 v[36:37], v[58:59], v[36:37]
	s_add_i32 s2, s78, s50
	v_pk_add_f32 v[36:37], v[64:65], v[36:37]
	v_lshlrev_b64 v[2:3], 8, v[2:3]
	v_pk_add_f32 v[36:37], v[66:67], v[36:37]
	s_mul_hi_i32 s43, s2, 0x201000
	v_pk_add_f32 v[36:37], v[46:47], v[36:37]
	s_mul_i32 s42, s2, 0x201000
	v_pk_add_f32 v[36:37], v[58:59], v[36:37]
	v_mad_i64_i32 v[2:3], s[2:3], s2, v208, v[2:3]
	v_pk_add_f32 v[36:37], v[64:65], v[36:37]
	s_lshr_b32 s83, s86, 6
	v_pk_add_f32 v[36:37], v[66:67], v[36:37]
	s_mul_hi_i32 s45, s44, 0x2010
	v_pk_add_f32 v[198:199], v[46:47], v[36:37]
	v_cvt_pk_bf16_f32 v36, v50, v52
	v_cvt_pk_bf16_f32 v37, v54, v56
	v_cvt_pk_bf16_f32 v38, v58, v64
	v_cvt_pk_bf16_f32 v39, v66, v46
	v_cvt_pk_bf16_f32 v40, v58, v64
	v_cvt_pk_bf16_f32 v41, v66, v46
	v_cvt_pk_bf16_f32 v42, v58, v64
	v_cvt_pk_bf16_f32 v43, v66, v46
	v_lshlrev_b32_e32 v46, 3, v44
	v_and_b32_e32 v46, 24, v46
	v_add3_u32 v215, 0, v0, v46
	v_and_b32_e32 v0, 7, v44
	v_lshl_or_b32 v2, v0, 4, v2
	v_sub_u32_e32 v0, v69, v45
	v_lshl_add_u64 v[202:203], s[8:9], 0, v[2:3]
	s_nop 0
	v_readfirstlane_b32 s100, v202
	v_readfirstlane_b32 s101, v203
	s_sub_u32 s100, s100, 0x4110000
	s_subb_u32 s101, s101, 0
	v_subrev_u32_e32 v202, s100, v202
	v_add_u32_e32 v202, 0xfbf00000, v202
	v_add_u32_e32 v203, 0x40fc000, v202
	v_subrev_u32_e32 v0, s1, v0
	v_mov_b32_e32 v2, v1
	v_mov_b32_e32 v3, v1
	v_cvt_pk_bf16_f32 v60, v51, v53
	v_cvt_pk_bf16_f32 v61, v55, v57
	v_cvt_pk_bf16_f32 v62, v59, v65
	v_cvt_pk_bf16_f32 v63, v67, v47
	v_cvt_pk_bf16_f32 v84, v59, v65
	v_cvt_pk_bf16_f32 v85, v67, v47
	v_cvt_pk_bf16_f32 v86, v59, v65
	v_cvt_pk_bf16_f32 v87, v67, v47
	v_subrev_u32_e32 v217, s0, v0
	v_mov_b32_e32 v0, v1
	v_mov_b64_e32 v[130:131], v[2:3]
	v_mov_b64_e32 v[126:127], v[2:3]
	v_mov_b64_e32 v[118:119], v[2:3]
	v_mov_b64_e32 v[106:107], v[2:3]
	v_mov_b64_e32 v[90:91], v[2:3]
	v_mov_b64_e32 v[82:83], v[2:3]
	v_mov_b64_e32 v[70:71], v[2:3]
	v_mov_b64_e32 v[58:59], v[2:3]
	v_mov_b64_e32 v[122:123], v[2:3]
	v_mov_b64_e32 v[110:111], v[2:3]
	v_mov_b64_e32 v[102:103], v[2:3]
	v_mov_b64_e32 v[98:99], v[2:3]
	v_mov_b64_e32 v[78:79], v[2:3]
	v_mov_b64_e32 v[66:67], v[2:3]
	v_mov_b64_e32 v[54:55], v[2:3]
	v_mov_b64_e32 v[50:51], v[2:3]
	s_mulk_i32 s44, 0x2010
	s_add_i32 s84, s82, 3
	s_add_i32 s85, s83, 2
	v_add_u32_e32 v216, 0xd000, v215
	s_addk_i32 s86, 0xff47
	s_mov_b32 s87, 0
	v_mov_b64_e32 v[128:129], v[0:1]
	v_mov_b64_e32 v[124:125], v[0:1]
	v_mov_b64_e32 v[116:117], v[0:1]
	v_mov_b64_e32 v[104:105], v[0:1]
	v_mov_b64_e32 v[88:89], v[0:1]
	v_mov_b64_e32 v[80:81], v[0:1]
	v_mov_b64_e32 v[68:69], v[0:1]
	v_mov_b64_e32 v[56:57], v[0:1]
	v_mov_b64_e32 v[120:121], v[0:1]
	v_mov_b64_e32 v[108:109], v[0:1]
	v_mov_b64_e32 v[100:101], v[0:1]
	v_mov_b64_e32 v[96:97], v[0:1]
	v_mov_b64_e32 v[76:77], v[0:1]
	v_mov_b64_e32 v[64:65], v[0:1]
	v_mov_b64_e32 v[52:53], v[0:1]
	v_mov_b64_e32 v[48:49], v[0:1]
	s_mov_b32 s89, 0

.Lq1_body:
	global_load_dwordx4 v[28:31], v202, s[100:101] offset:-128
	global_load_dwordx4 v[32:35], v202, s[100:101]
	global_load_dwordx4 v[4:7], v203, s[100:101] offset:-128
	global_load_dwordx4 v[12:15], v203, s[100:101]
	ds_read_b128 v[44:47], v214 offset:35840
	ds_read_b128 v[72:75], v214 offset:35904
	ds_read_b128 v[92:95], v214 offset:40192
	ds_read_b128 v[112:115], v214 offset:40256
	ds_read_b128 v[132:135], v214 offset:44544
	ds_read_b128 v[148:151], v214 offset:44608
	ds_read_b128 v[136:139], v214 offset:48896
	ds_read_b128 v[152:155], v214 offset:48960
	s_waitcnt lgkmcnt(7)
	v_mfma_f32_16x16x32_bf16 v[140:143], v[44:47], v[8:11], 0
	v_mfma_f32_16x16x32_bf16 v[44:47], v[44:47], v[20:23], 0
	s_waitcnt lgkmcnt(1)
	v_mfma_f32_16x16x32_bf16 v[156:159], v[92:95], v[8:11], 0
	v_mfma_f32_16x16x32_bf16 v[92:95], v[92:95], v[20:23], 0
	v_mfma_f32_16x16x32_bf16 v[160:163], v[132:135], v[8:11], 0
	v_mfma_f32_16x16x32_bf16 v[132:135], v[132:135], v[20:23], 0
	v_mfma_f32_16x16x32_bf16 v[164:167], v[136:139], v[8:11], 0
	v_mfma_f32_16x16x32_bf16 v[168:171], v[136:139], v[20:23], 0
	v_mfma_f32_16x16x32_bf16 v[144:147], v[72:75], v[16:19], v[140:143]
	v_mfma_f32_16x16x32_bf16 v[136:139], v[72:75], v[24:27], v[44:47]
	v_mfma_f32_16x16x32_bf16 v[44:47], v[112:115], v[16:19], v[156:159]
	v_mfma_f32_16x16x32_bf16 v[92:95], v[112:115], v[24:27], v[92:95]
	v_mfma_f32_16x16x32_bf16 v[140:143], v[148:151], v[16:19], v[160:163]
	v_mfma_f32_16x16x32_bf16 v[132:135], v[148:151], v[24:27], v[132:135]
	s_waitcnt lgkmcnt(0)
	v_mfma_f32_16x16x32_bf16 v[72:75], v[152:155], v[16:19], v[164:167]
	v_mfma_f32_16x16x32_bf16 v[112:115], v[152:155], v[24:27], v[168:171]
	s_cmp_eq_u32 s98, 0
	s_cbranch_scc1 .LBB0_859
	v_sub_f32_e32 v147, v147, v196
	v_sub_f32_e32 v146, v146, v196
	v_sub_f32_e32 v145, v145, v196
	v_sub_f32_e32 v144, v144, v196
	v_sub_f32_e32 v47, v47, v196
	v_sub_f32_e32 v46, v46, v196
	v_sub_f32_e32 v45, v45, v196
	v_sub_f32_e32 v44, v44, v196
	v_sub_f32_e32 v143, v143, v196
	v_sub_f32_e32 v142, v142, v196
	v_sub_f32_e32 v141, v141, v196
	v_sub_f32_e32 v140, v140, v196
	v_sub_f32_e32 v75, v75, v196
	v_sub_f32_e32 v74, v74, v196
	v_sub_f32_e32 v73, v73, v196
	v_sub_f32_e32 v72, v72, v196
	v_sub_f32_e32 v139, v139, v197
	v_sub_f32_e32 v138, v138, v197
	v_sub_f32_e32 v137, v137, v197
	v_sub_f32_e32 v136, v136, v197
	v_sub_f32_e32 v95, v95, v197
	v_sub_f32_e32 v94, v94, v197
	v_sub_f32_e32 v93, v93, v197
	v_sub_f32_e32 v92, v92, v197
	v_sub_f32_e32 v135, v135, v197
	v_sub_f32_e32 v134, v134, v197
	v_sub_f32_e32 v133, v133, v197
	v_sub_f32_e32 v132, v132, v197
	v_sub_f32_e32 v115, v115, v197
	v_sub_f32_e32 v114, v114, v197
	v_sub_f32_e32 v113, v113, v197
	v_sub_f32_e32 v112, v112, v197

.LBB0_865:
	v_pk_add_f32 v[2:3], v[198:199], v[2:3]
	s_waitcnt vmcnt(0)
	v_pk_add_f32 v[2:3], v[222:223], v[2:3]
	ds_write_b128 v211, v[28:31]
	v_pk_add_f32 v[2:3], v[224:225], v[2:3]
	ds_write_b128 v211, v[32:35] offset:128
	v_pk_add_f32 v[2:3], v[122:123], v[2:3]
	ds_write_b128 v213, v[4:7] offset:53248
	v_pk_add_f32 v[2:3], v[226:227], v[2:3]
	ds_write_b128 v213, v[12:15] offset:53376
	v_pk_add_f32 v[2:3], v[110:111], v[2:3]
	v_cvt_pk_bf16_f32 v112, v97, v231
	v_pk_add_f32 v[2:3], v[228:229], v[2:3]
	v_cvt_pk_bf16_f32 v113, v233, v79
	v_pk_add_f32 v[2:3], v[100:101], v[2:3]
	v_cvt_pk_bf16_f32 v114, v235, v67
	v_pk_add_f32 v[2:3], v[96:97], v[2:3]
	v_cvt_pk_bf16_f32 v115, v237, v55
	v_pk_add_f32 v[2:3], v[230:231], v[2:3]
	s_add_u32 s100, s100, 0x4000
	v_pk_add_f32 v[2:3], v[232:233], v[2:3]
	s_addc_u32 s101, s101, 0
	v_pk_add_f32 v[2:3], v[78:79], v[2:3]
	s_cmp_lt_u32 s89, s82
	v_pk_add_f32 v[2:3], v[234:235], v[2:3]
	s_nop 0
	v_pk_add_f32 v[2:3], v[66:67], v[2:3]
	s_nop 0
	v_pk_add_f32 v[2:3], v[236:237], v[2:3]
	s_nop 0
	v_pk_add_f32 v[198:199], v[54:55], v[2:3]
.LBB0_866:
	s_waitcnt lgkmcnt(0)
	s_barrier
	s_cbranch_scc0 .Lq1_h2_nok
	global_load_dwordx4 v[28:31], v202, s[100:101] offset:-128
	global_load_dwordx4 v[32:35], v202, s[100:101]
.Lq1_h2_nok:
	global_load_dwordx4 v[4:7], v203, s[100:101] offset:-128
	global_load_dwordx4 v[12:15], v203, s[100:101]
	s_cmp_ge_u32 s89, s83
	s_cbranch_scc1 .Lq1_h2_pvonly
	ds_read_b128 v[36:39], v214
	ds_read_b128 v[40:43], v214 offset:64
	ds_read_b128 v[60:63], v214 offset:4352
	ds_read_b128 v[84:87], v214 offset:4416
	ds_read_b128 v[64:67], v214 offset:8704
	ds_read_b128 v[124:127], v214 offset:8768
	ds_read_b128 v[108:111], v214 offset:13056
	ds_read_b128 v[100:103], v214 offset:13120
	s_waitcnt lgkmcnt(7)
	v_mfma_f32_16x16x32_bf16 v[120:123], v[36:39], v[8:11], 0
	v_mfma_f32_16x16x32_bf16 v[36:39], v[36:39], v[20:23], 0
	s_waitcnt lgkmcnt(1)
	v_mfma_f32_16x16x32_bf16 v[116:119], v[60:63], v[8:11], 0
	v_mfma_f32_16x16x32_bf16 v[60:63], v[60:63], v[20:23], 0
	v_mfma_f32_16x16x32_bf16 v[96:99], v[64:67], v[8:11], 0
	v_mfma_f32_16x16x32_bf16 v[64:67], v[64:67], v[20:23], 0
	v_mfma_f32_16x16x32_bf16 v[104:107], v[108:111], v[8:11], 0
	v_mfma_f32_16x16x32_bf16 v[76:79], v[108:111], v[20:23], 0
	v_mfma_f32_16x16x32_bf16 v[128:131], v[40:43], v[16:19], v[120:123]
	v_mfma_f32_16x16x32_bf16 v[108:111], v[40:43], v[24:27], v[36:39]
	v_mfma_f32_16x16x32_bf16 v[36:39], v[84:87], v[16:19], v[116:119]
	v_mfma_f32_16x16x32_bf16 v[60:63], v[84:87], v[24:27], v[60:63]
	v_mfma_f32_16x16x32_bf16 v[120:123], v[124:127], v[16:19], v[96:99]
	v_mfma_f32_16x16x32_bf16 v[64:67], v[124:127], v[24:27], v[64:67]
	s_waitcnt lgkmcnt(0)
	v_mfma_f32_16x16x32_bf16 v[40:43], v[100:103], v[16:19], v[104:107]
	v_mfma_f32_16x16x32_bf16 v[84:87], v[100:103], v[24:27], v[76:79]
	s_cmp_eq_u32 s98, 0
	s_cbranch_scc1 .LBB0_875
	v_sub_f32_e32 v131, v131, v196
	v_sub_f32_e32 v130, v130, v196
	v_sub_f32_e32 v129, v129, v196
	v_sub_f32_e32 v128, v128, v196
	v_sub_f32_e32 v39, v39, v196
	v_sub_f32_e32 v38, v38, v196
	v_sub_f32_e32 v37, v37, v196
	v_sub_f32_e32 v36, v36, v196
	v_sub_f32_e32 v123, v123, v196
	v_sub_f32_e32 v122, v122, v196
	v_sub_f32_e32 v121, v121, v196
	v_sub_f32_e32 v120, v120, v196
	v_sub_f32_e32 v43, v43, v196
	v_sub_f32_e32 v42, v42, v196
	v_sub_f32_e32 v41, v41, v196
	v_sub_f32_e32 v40, v40, v196
	v_sub_f32_e32 v111, v111, v197
	v_sub_f32_e32 v110, v110, v197
	v_sub_f32_e32 v109, v109, v197
	v_sub_f32_e32 v108, v108, v197
	v_sub_f32_e32 v63, v63, v197
	v_sub_f32_e32 v62, v62, v197
	v_sub_f32_e32 v61, v61, v197
	v_sub_f32_e32 v60, v60, v197
	v_sub_f32_e32 v67, v67, v197
	v_sub_f32_e32 v66, v66, v197
	v_sub_f32_e32 v65, v65, v197
	v_sub_f32_e32 v64, v64, v197
	v_sub_f32_e32 v87, v87, v197
	v_sub_f32_e32 v86, v86, v197
	v_sub_f32_e32 v85, v85, v197
	v_sub_f32_e32 v84, v84, v197

.LBB0_881:
	v_pk_add_f32 v[2:3], v[198:199], v[2:3]
	s_waitcnt vmcnt(0)
	v_pk_add_f32 v[2:3], v[222:223], v[2:3]
	ds_write_b128 v211, v[28:31] offset:35840
	v_pk_add_f32 v[2:3], v[224:225], v[2:3]
	ds_write_b128 v211, v[32:35] offset:35968
	v_pk_add_f32 v[2:3], v[142:143], v[2:3]
	ds_write_b128 v213, v[4:7] offset:17408
	v_pk_add_f32 v[2:3], v[226:227], v[2:3]
	ds_write_b128 v213, v[12:15] offset:17536
	v_pk_add_f32 v[2:3], v[138:139], v[2:3]
	v_cvt_pk_bf16_f32 v84, v161, v231
	v_pk_add_f32 v[2:3], v[228:229], v[2:3]
	v_cvt_pk_bf16_f32 v85, v233, v171
	v_pk_add_f32 v[2:3], v[154:155], v[2:3]
	v_cvt_pk_bf16_f32 v86, v235, v135
	v_pk_add_f32 v[2:3], v[160:161], v[2:3]
	v_cvt_pk_bf16_f32 v87, v237, v183
	v_pk_add_f32 v[2:3], v[230:231], v[2:3]
	s_add_u32 s100, s100, 0x4000
	v_pk_add_f32 v[2:3], v[232:233], v[2:3]
	s_addc_u32 s101, s101, 0
	v_pk_add_f32 v[2:3], v[170:171], v[2:3]
	s_addk_i32 s87, 0x80
	v_pk_add_f32 v[2:3], v[234:235], v[2:3]
	s_mov_b32 s89, s88
	v_pk_add_f32 v[2:3], v[134:135], v[2:3]
	s_add_i32 s88, s88, 2
	v_pk_add_f32 v[2:3], v[236:237], v[2:3]
	s_cmp_lt_u32 s88, s84
	v_pk_add_f32 v[198:199], v[182:183], v[2:3]

.Lq1_h2_pvonly:
	ds_read_b64_tr_b16 v[64:65], v215 offset:53248
	ds_read_b64_tr_b16 v[108:109], v215 offset:53280
	ds_read_b64_tr_b16 v[120:121], v215 offset:53312
	ds_read_b64_tr_b16 v[128:129], v215 offset:53344
	ds_read_b64_tr_b16 v[66:67], v215 offset:57856
	ds_read_b64_tr_b16 v[110:111], v215 offset:57888
	ds_read_b64_tr_b16 v[122:123], v215 offset:57920
	ds_read_b64_tr_b16 v[130:131], v215 offset:57952
	s_waitcnt lgkmcnt(3)
	v_mfma_f32_16x16x32_bf16 v[124:127], v[44:47], v[64:67], v[144:147]
	v_mfma_f32_16x16x32_bf16 v[64:67], v[92:95], v[64:67], v[140:143]
	s_waitcnt lgkmcnt(2)
	v_mfma_f32_16x16x32_bf16 v[100:103], v[44:47], v[108:111], v[148:151]
	v_mfma_f32_16x16x32_bf16 v[108:111], v[92:95], v[108:111], v[136:139]
	s_waitcnt lgkmcnt(1)
	v_mfma_f32_16x16x32_bf16 v[116:119], v[44:47], v[120:123], v[156:159]
	v_mfma_f32_16x16x32_bf16 v[96:99], v[92:95], v[120:123], v[152:155]
	s_waitcnt lgkmcnt(0)
	v_mfma_f32_16x16x32_bf16 v[104:107], v[44:47], v[128:131], v[164:167]
	v_mfma_f32_16x16x32_bf16 v[76:79], v[92:95], v[128:131], v[160:163]
	ds_read_b64_tr_b16 v[120:121], v215 offset:53376
	ds_read_b64_tr_b16 v[128:129], v215 offset:53408
	ds_read_b64_tr_b16 v[88:89], v215 offset:53440
	ds_read_b64_tr_b16 v[80:81], v215 offset:53472
	ds_read_b64_tr_b16 v[122:123], v215 offset:57984
	ds_read_b64_tr_b16 v[130:131], v215 offset:58016
	ds_read_b64_tr_b16 v[90:91], v215 offset:58048
	ds_read_b64_tr_b16 v[82:83], v215 offset:58080
	s_waitcnt lgkmcnt(3)
	v_mfma_f32_16x16x32_bf16 v[52:55], v[44:47], v[120:123], v[172:175]
	v_mfma_f32_16x16x32_bf16 v[68:71], v[92:95], v[120:123], v[168:171]
	s_waitcnt lgkmcnt(2)
	v_mfma_f32_16x16x32_bf16 v[48:51], v[44:47], v[128:131], v[176:179]
	v_mfma_f32_16x16x32_bf16 v[56:59], v[92:95], v[128:131], v[132:135]
	s_waitcnt lgkmcnt(1)
	v_mfma_f32_16x16x32_bf16 v[218:221], v[44:47], v[88:91], v[184:187]
	v_mfma_f32_16x16x32_bf16 v[222:225], v[92:95], v[88:91], v[180:183]
	s_waitcnt lgkmcnt(0)
	v_mfma_f32_16x16x32_bf16 v[226:229], v[44:47], v[80:83], v[192:195]
	v_mfma_f32_16x16x32_bf16 v[230:233], v[92:95], v[80:83], v[188:191]
	ds_read_b64_tr_b16 v[120:121], v215 offset:62464
	ds_read_b64_tr_b16 v[88:89], v215 offset:62496
	ds_read_b64_tr_b16 v[80:81], v215 offset:62528
	ds_read_b64_tr_b16 v[234:235], v215 offset:62560
	ds_read_b64_tr_b16 v[122:123], v216 offset:13824
	ds_read_b64_tr_b16 v[90:91], v216 offset:13856
	ds_read_b64_tr_b16 v[82:83], v216 offset:13888
	ds_read_b64_tr_b16 v[236:237], v216 offset:13920
	s_waitcnt lgkmcnt(3)
	v_mfma_f32_16x16x32_bf16 v[128:131], v[72:75], v[120:123], v[124:127]
	v_mfma_f32_16x16x32_bf16 v[120:123], v[112:115], v[120:123], v[64:67]
	s_waitcnt lgkmcnt(2)
	v_mfma_f32_16x16x32_bf16 v[124:127], v[72:75], v[88:91], v[100:103]
	v_mfma_f32_16x16x32_bf16 v[108:111], v[112:115], v[88:91], v[108:111]
	s_waitcnt lgkmcnt(1)
	v_mfma_f32_16x16x32_bf16 v[116:119], v[72:75], v[80:83], v[116:119]
	v_mfma_f32_16x16x32_bf16 v[100:103], v[112:115], v[80:83], v[96:99]
	s_waitcnt lgkmcnt(0)
	v_mfma_f32_16x16x32_bf16 v[104:107], v[72:75], v[234:237], v[104:107]
	v_mfma_f32_16x16x32_bf16 v[96:99], v[112:115], v[234:237], v[76:79]
	ds_read_b64_tr_b16 v[64:65], v215 offset:62592
	ds_read_b64_tr_b16 v[234:235], v215 offset:62624
	ds_read_b64_tr_b16 v[238:239], v215 offset:62656
	ds_read_b64_tr_b16 v[242:243], v215 offset:62688
	ds_read_b64_tr_b16 v[66:67], v216 offset:13952
	ds_read_b64_tr_b16 v[236:237], v216 offset:13984
	ds_read_b64_tr_b16 v[240:241], v216 offset:14016
	ds_read_b64_tr_b16 v[244:245], v216 offset:14048
	s_waitcnt lgkmcnt(3)
	v_mfma_f32_16x16x32_bf16 v[88:91], v[72:75], v[64:67], v[52:55]
	v_mfma_f32_16x16x32_bf16 v[76:79], v[112:115], v[64:67], v[68:71]
	s_waitcnt lgkmcnt(2)
	v_mfma_f32_16x16x32_bf16 v[80:83], v[72:75], v[234:237], v[48:51]
	v_mfma_f32_16x16x32_bf16 v[64:67], v[112:115], v[234:237], v[56:59]
	s_waitcnt lgkmcnt(1)
	v_mfma_f32_16x16x32_bf16 v[68:71], v[72:75], v[238:241], v[218:221]
	v_mfma_f32_16x16x32_bf16 v[52:55], v[112:115], v[238:241], v[222:225]
	s_waitcnt lgkmcnt(0)
	v_mfma_f32_16x16x32_bf16 v[56:59], v[72:75], v[242:245], v[226:229]
	v_mfma_f32_16x16x32_bf16 v[48:51], v[112:115], v[242:245], v[230:233]
	s_mov_b64 s[2:3], 0
	s_waitcnt vmcnt(0)
	ds_write_b128 v211, v[28:31] offset:35840
	ds_write_b128 v211, v[32:35] offset:35968
	ds_write_b128 v213, v[4:7] offset:17408
	ds_write_b128 v213, v[12:15] offset:17536
	s_add_u32 s100, s100, 0x4000
	s_addc_u32 s101, s101, 0
	s_addk_i32 s87, 0x80
	s_mov_b32 s89, s88
	s_add_i32 s88, s88, 2
	s_cmp_lt_u32 s88, s84
	s_branch .LBB0_882

; template <bool SAMPLE> __device__ __forceinline__ void attn_unit16(const Ctx& c, LAS unsigned char* lds, int b, int h, int qb, int wave_s) {
;     ...
;     for (int j = 0; j < ntiles; j += 2) {
;         ITER16(j, pfa, pfb, 0, 1);
;         if (j + 1 < ntiles) ITER16(j + 1, pfb, pfa, 1, 0);
;     }
.Lq1_last_bar:
	s_waitcnt lgkmcnt(0)
	s_barrier
	s_addk_i32 s87, 0x80
